# per-unit accumulator zeroing with 64 v_mov_b64 instead of 128 v_mov_b32 (all four GEMM unit loops)
# baseline (speedup 1.0000x reference)
; template <class Epi, class Sched, bool ALIGN_EPI = false, bool SP2 = false, bool HALFM = false>
; __device__ __forceinline__ void gemm_phase(PG8_LAS unsigned char* lds, const Gemm g, const Sched& S, const Epi& E) {
;     ...
; #pragma unroll
;         for (int a = 0; a < 2; ++a)
; #pragma unroll
;             for (int b = 0; b < 2; ++b)
; #pragma unroll
;                 for (int m = 0; m < 4; ++m)
; #pragma unroll
;                     for (int n = 0; n < 2; ++n) acc[a][b][m][n] = (f32x4){0.f, 0.f, 0.f, 0.f};
;         cur = nxt; cA = nA; cB = nB; ++ui;
.LBB0_177:
	s_ashr_i32 s11, s10, 31
	s_xor_b64 s[16:17], s[18:19], -1
	s_lshl_b64 s[12:13], s[10:11], 19
	s_add_u32 s12, s30, s12
	s_addc_u32 s13, s31, s13
	s_and_b64 s[14:15], exec, s[18:19]
	s_cselect_b32 s11, s23, s13
	s_cselect_b32 s58, s22, s12
	s_ashr_i32 s9, s8, 31
	s_lshl_b64 s[14:15], s[8:9], 19
	s_add_u32 s14, s29, s14
	s_addc_u32 s15, s45, s15
	s_and_b64 s[20:21], exec, s[18:19]
	s_cselect_b32 s9, s25, s15
	s_cselect_b32 s59, s24, s14
	s_lshl_b32 s60, s10, 8
	s_lshl_b32 s26, s54, 10
	s_cmp_eq_u32 s10, s28
	s_cselect_b64 s[20:21], -1, 0
	s_add_i32 s61, s26, 0
	s_add_i32 s61, s61, 0x24900
	s_add_u32 s22, s22, 0x40080
	s_addc_u32 s23, s23, 0
	s_add_u32 s62, s24, 0x100
	v_mov_b32_e32 v0, 0
	s_addc_u32 s63, s25, 0
	s_mov_b32 s64, -2
	v_mov_b32_e32 v1, 0
	v_mov_b64_e32 v[2:3], 0
	v_mov_b64_e32 v[4:5], 0
	v_mov_b64_e32 v[6:7], 0
	v_mov_b64_e32 v[8:9], 0
	v_mov_b64_e32 v[10:11], 0
	v_mov_b64_e32 v[12:13], 0
	v_mov_b64_e32 v[14:15], 0
	v_mov_b64_e32 v[16:17], 0
	v_mov_b64_e32 v[18:19], 0
	v_mov_b64_e32 v[20:21], 0
	v_mov_b64_e32 v[22:23], 0
	v_mov_b64_e32 v[24:25], 0
	v_mov_b64_e32 v[26:27], 0
	v_mov_b64_e32 v[28:29], 0
	v_mov_b64_e32 v[30:31], 0
	v_mov_b64_e32 v[32:33], 0
	v_mov_b64_e32 v[34:35], 0
	v_mov_b64_e32 v[36:37], 0
	v_mov_b64_e32 v[38:39], 0
	v_mov_b64_e32 v[40:41], 0
	v_mov_b64_e32 v[42:43], 0
	v_mov_b64_e32 v[44:45], 0
	v_mov_b64_e32 v[46:47], 0
	v_mov_b64_e32 v[48:49], 0
	v_mov_b64_e32 v[50:51], 0
	v_mov_b64_e32 v[52:53], 0
	v_mov_b64_e32 v[54:55], 0
	v_mov_b64_e32 v[56:57], 0
	v_mov_b64_e32 v[58:59], 0
	v_mov_b64_e32 v[60:61], 0
	v_mov_b64_e32 v[62:63], 0
	v_mov_b64_e32 v[64:65], 0
	v_mov_b64_e32 v[66:67], 0
	v_mov_b64_e32 v[68:69], 0
	v_mov_b64_e32 v[70:71], 0
	v_mov_b64_e32 v[72:73], 0
	v_mov_b64_e32 v[74:75], 0
	v_mov_b64_e32 v[76:77], 0
	v_mov_b64_e32 v[78:79], 0
	v_mov_b64_e32 v[82:83], 0
	v_mov_b64_e32 v[84:85], 0
	v_mov_b64_e32 v[86:87], 0
	v_mov_b64_e32 v[88:89], 0
	v_mov_b64_e32 v[90:91], 0
	v_mov_b64_e32 v[92:93], 0
	v_mov_b64_e32 v[94:95], 0
	v_mov_b64_e32 v[96:97], 0
	v_mov_b64_e32 v[98:99], 0
	v_mov_b64_e32 v[100:101], 0
	v_mov_b64_e32 v[102:103], 0
	v_mov_b64_e32 v[104:105], 0
	v_mov_b64_e32 v[106:107], 0
	v_mov_b64_e32 v[108:109], 0
	v_mov_b64_e32 v[110:111], 0
	v_mov_b64_e32 v[112:113], 0
	v_mov_b64_e32 v[114:115], 0
	v_mov_b64_e32 v[116:117], 0
	v_mov_b64_e32 v[118:119], 0
	v_mov_b64_e32 v[120:121], 0
	v_mov_b64_e32 v[122:123], 0
	v_mov_b64_e32 v[124:125], 0
	v_mov_b64_e32 v[126:127], 0
	v_mov_b64_e32 v[128:129], 0
	s_branch .LBB0_180

; template <class Epi, class Sched, bool ALIGN_EPI = false, bool SP2 = false, bool HALFM = false>
; __device__ __forceinline__ void gemm_phase(PG8_LAS unsigned char* lds, const Gemm g, const Sched& S, const Epi& E) {
;     ...
; #pragma unroll
;         for (int a = 0; a < 2; ++a)
; #pragma unroll
;             for (int b = 0; b < 2; ++b)
; #pragma unroll
;                 for (int m = 0; m < 4; ++m)
; #pragma unroll
;                     for (int n = 0; n < 2; ++n) acc[a][b][m][n] = (f32x4){0.f, 0.f, 0.f, 0.f};
;         cur = nxt; cA = nA; cB = nB; ++ui;
.LBB0_273:
	s_add_u32 s58, s22, 0x100
	v_mov_b32_e32 v0, 0
	s_addc_u32 s59, s23, 0
	s_mov_b32 s60, -2
	s_waitcnt lgkmcnt(0)
	v_mov_b32_e32 v1, 0
	v_mov_b64_e32 v[2:3], 0
	v_mov_b64_e32 v[4:5], 0
	v_mov_b64_e32 v[6:7], 0
	v_mov_b64_e32 v[8:9], 0
	v_mov_b64_e32 v[10:11], 0
	v_mov_b64_e32 v[12:13], 0
	v_mov_b64_e32 v[14:15], 0
	v_mov_b64_e32 v[16:17], 0
	v_mov_b64_e32 v[18:19], 0
	v_mov_b64_e32 v[20:21], 0
	v_mov_b64_e32 v[22:23], 0
	v_mov_b64_e32 v[24:25], 0
	v_mov_b64_e32 v[26:27], 0
	v_mov_b64_e32 v[28:29], 0
	v_mov_b64_e32 v[30:31], 0
	v_mov_b64_e32 v[32:33], 0
	v_mov_b64_e32 v[34:35], 0
	v_mov_b64_e32 v[36:37], 0
	v_mov_b64_e32 v[38:39], 0
	v_mov_b64_e32 v[40:41], 0
	v_mov_b64_e32 v[42:43], 0
	v_mov_b64_e32 v[44:45], 0
	v_mov_b64_e32 v[46:47], 0
	v_mov_b64_e32 v[48:49], 0
	v_mov_b64_e32 v[50:51], 0
	v_mov_b64_e32 v[52:53], 0
	v_mov_b64_e32 v[54:55], 0
	v_mov_b64_e32 v[56:57], 0
	v_mov_b64_e32 v[58:59], 0
	v_mov_b64_e32 v[60:61], 0
	v_mov_b64_e32 v[62:63], 0
	v_mov_b64_e32 v[64:65], 0
	v_mov_b64_e32 v[66:67], 0
	v_mov_b64_e32 v[68:69], 0
	v_mov_b64_e32 v[70:71], 0
	v_mov_b64_e32 v[72:73], 0
	v_mov_b64_e32 v[74:75], 0
	v_mov_b64_e32 v[76:77], 0
	v_mov_b64_e32 v[78:79], 0
	v_mov_b64_e32 v[82:83], 0
	v_mov_b64_e32 v[84:85], 0
	v_mov_b64_e32 v[86:87], 0
	v_mov_b64_e32 v[88:89], 0
	v_mov_b64_e32 v[90:91], 0
	v_mov_b64_e32 v[92:93], 0
	v_mov_b64_e32 v[94:95], 0
	v_mov_b64_e32 v[96:97], 0
	v_mov_b64_e32 v[98:99], 0
	v_mov_b64_e32 v[100:101], 0
	v_mov_b64_e32 v[102:103], 0
	v_mov_b64_e32 v[104:105], 0
	v_mov_b64_e32 v[106:107], 0
	v_mov_b64_e32 v[108:109], 0
	v_mov_b64_e32 v[110:111], 0
	v_mov_b64_e32 v[112:113], 0
	v_mov_b64_e32 v[114:115], 0
	v_mov_b64_e32 v[116:117], 0
	v_mov_b64_e32 v[118:119], 0
	v_mov_b64_e32 v[120:121], 0
	v_mov_b64_e32 v[122:123], 0
	v_mov_b64_e32 v[124:125], 0
	v_mov_b64_e32 v[126:127], 0
	v_mov_b64_e32 v[128:129], 0

; template <class Epi, class Sched, bool ALIGN_EPI = false, bool SP2 = false, bool HALFM = false>
; __device__ __forceinline__ void gemm_phase(PG8_LAS unsigned char* lds, const Gemm g, const Sched& S, const Epi& E) {
;     ...
; #pragma unroll
;         for (int a = 0; a < 2; ++a)
; #pragma unroll
;             for (int b = 0; b < 2; ++b)
; #pragma unroll
;                 for (int m = 0; m < 4; ++m)
; #pragma unroll
;                     for (int n = 0; n < 2; ++n) acc[a][b][m][n] = (f32x4){0.f, 0.f, 0.f, 0.f};
;         cur = nxt; cA = nA; cB = nB; ++ui;
.LBB0_411:
	s_ashr_i32 s15, s14, 31
	s_xor_b64 s[20:21], s[0:1], -1
	s_lshl_b64 s[16:17], s[14:15], 19
	s_add_u32 s16, s30, s16
	s_addc_u32 s17, s31, s17
	s_and_b64 s[18:19], exec, s[0:1]
	s_cselect_b32 s15, s25, s17
	s_cselect_b32 s60, s24, s16
	s_ashr_i32 s13, s12, 31
	s_lshl_b64 s[18:19], s[12:13], 19
	s_add_u32 s18, s46, s18
	s_addc_u32 s19, s47, s19
	s_and_b64 s[22:23], exec, s[0:1]
	s_cselect_b32 s13, s27, s19
	s_cselect_b32 s61, s26, s18
	s_lshl_b32 s62, s14, 8
	s_lshl_b32 s28, s56, 10
	s_cmp_eq_u32 s14, s45
	s_cselect_b64 s[22:23], -1, 0
	s_add_i32 s63, s28, 0
	s_add_i32 s63, s63, 0x24900
	s_add_u32 s24, s24, 0x40080
	s_addc_u32 s25, s25, 0
	s_add_u32 s64, s26, 0x100
	v_mov_b32_e32 v0, 0
	s_addc_u32 s65, s27, 0
	s_mov_b32 s66, -2
	v_mov_b32_e32 v1, 0
	v_mov_b64_e32 v[2:3], 0
	v_mov_b64_e32 v[4:5], 0
	v_mov_b64_e32 v[6:7], 0
	v_mov_b64_e32 v[8:9], 0
	v_mov_b64_e32 v[10:11], 0
	v_mov_b64_e32 v[12:13], 0
	s_waitcnt vmcnt(0)
	v_mov_b64_e32 v[14:15], 0
	v_mov_b64_e32 v[16:17], 0
	v_mov_b64_e32 v[18:19], 0
	v_mov_b64_e32 v[20:21], 0
	v_mov_b64_e32 v[22:23], 0
	v_mov_b64_e32 v[24:25], 0
	v_mov_b64_e32 v[26:27], 0
	v_mov_b64_e32 v[28:29], 0
	s_waitcnt lgkmcnt(0)
	v_mov_b64_e32 v[30:31], 0
	v_mov_b64_e32 v[32:33], 0
	v_mov_b64_e32 v[34:35], 0
	v_mov_b64_e32 v[36:37], 0
	v_mov_b64_e32 v[38:39], 0
	v_mov_b64_e32 v[40:41], 0
	v_mov_b64_e32 v[42:43], 0
	v_mov_b64_e32 v[44:45], 0
	v_mov_b64_e32 v[46:47], 0
	v_mov_b64_e32 v[48:49], 0
	v_mov_b64_e32 v[50:51], 0
	v_mov_b64_e32 v[52:53], 0
	v_mov_b64_e32 v[54:55], 0
	v_mov_b64_e32 v[56:57], 0
	v_mov_b64_e32 v[58:59], 0
	v_mov_b64_e32 v[60:61], 0
	v_mov_b64_e32 v[62:63], 0
	v_mov_b64_e32 v[64:65], 0
	v_mov_b64_e32 v[66:67], 0
	v_mov_b64_e32 v[68:69], 0
	v_mov_b64_e32 v[70:71], 0
	v_mov_b64_e32 v[72:73], 0
	v_mov_b64_e32 v[74:75], 0
	v_mov_b64_e32 v[76:77], 0
	v_mov_b64_e32 v[78:79], 0
	v_mov_b64_e32 v[82:83], 0
	v_mov_b64_e32 v[84:85], 0
	v_mov_b64_e32 v[86:87], 0
	v_mov_b64_e32 v[88:89], 0
	v_mov_b64_e32 v[90:91], 0
	v_mov_b64_e32 v[92:93], 0
	v_mov_b64_e32 v[94:95], 0
	v_mov_b64_e32 v[96:97], 0
	v_mov_b64_e32 v[98:99], 0
	v_mov_b64_e32 v[100:101], 0
	v_mov_b64_e32 v[102:103], 0
	v_mov_b64_e32 v[104:105], 0
	v_mov_b64_e32 v[106:107], 0
	v_mov_b64_e32 v[108:109], 0
	v_mov_b64_e32 v[110:111], 0
	v_mov_b64_e32 v[112:113], 0
	v_mov_b64_e32 v[114:115], 0
	v_mov_b64_e32 v[116:117], 0
	v_mov_b64_e32 v[118:119], 0
	v_mov_b64_e32 v[120:121], 0
	v_mov_b64_e32 v[122:123], 0
	v_mov_b64_e32 v[124:125], 0
	v_mov_b64_e32 v[126:127], 0
	v_mov_b64_e32 v[128:129], 0
	s_branch .LBB0_414

; template <class Epi, class Sched, bool ALIGN_EPI = false, bool SP2 = false, bool HALFM = false>
; __device__ __forceinline__ void gemm_phase(PG8_LAS unsigned char* lds, const Gemm g, const Sched& S, const Epi& E) {
;     ...
; #pragma unroll
;         for (int a = 0; a < 2; ++a)
; #pragma unroll
;             for (int b = 0; b < 2; ++b)
; #pragma unroll
;                 for (int m = 0; m < 4; ++m)
; #pragma unroll
;                     for (int n = 0; n < 2; ++n) acc[a][b][m][n] = (f32x4){0.f, 0.f, 0.f, 0.f};
;         cur = nxt; cA = nA; cB = nB; ++ui;
.LBB0_1164:
	s_ashr_i32 s13, s12, 31
	s_lshl_b64 s[14:15], s[12:13], 19
	s_add_u32 s14, s84, s14
	s_addc_u32 s15, s85, s15
	s_and_b64 s[16:17], s[22:23], exec
	s_cselect_b32 s13, s15, s19
	s_cselect_b32 s52, s14, s18
	s_ashr_i32 s11, s10, 31
	s_lshl_b64 s[16:17], s[10:11], 19
	s_add_u32 s16, s24, s16
	s_addc_u32 s17, s25, s17
	s_and_b64 s[22:23], s[22:23], exec
	s_cselect_b32 s11, s17, s21
	s_cselect_b32 s53, s16, s20
	s_add_u32 s18, s18, 0x40080
	s_addc_u32 s19, s19, 0
	s_add_u32 s54, s20, 0x100
	v_mov_b32_e32 v0, 0
	s_addc_u32 s55, s21, 0
	s_mov_b32 s56, -2
	s_waitcnt lgkmcnt(0)
	v_mov_b32_e32 v1, 0
	v_mov_b64_e32 v[2:3], 0
	v_mov_b64_e32 v[4:5], 0
	v_mov_b64_e32 v[6:7], 0
	v_mov_b64_e32 v[8:9], 0
	v_mov_b64_e32 v[10:11], 0
	v_mov_b64_e32 v[12:13], 0
	v_mov_b64_e32 v[14:15], 0
	v_mov_b64_e32 v[16:17], 0
	v_mov_b64_e32 v[18:19], 0
	v_mov_b64_e32 v[20:21], 0
	v_mov_b64_e32 v[22:23], 0
	v_mov_b64_e32 v[24:25], 0
	v_mov_b64_e32 v[26:27], 0
	v_mov_b64_e32 v[28:29], 0
	v_mov_b64_e32 v[30:31], 0
	v_mov_b64_e32 v[32:33], 0
	v_mov_b64_e32 v[34:35], 0
	v_mov_b64_e32 v[36:37], 0
	v_mov_b64_e32 v[38:39], 0
	v_mov_b64_e32 v[40:41], 0
	v_mov_b64_e32 v[42:43], 0
	v_mov_b64_e32 v[44:45], 0
	v_mov_b64_e32 v[46:47], 0
	v_mov_b64_e32 v[48:49], 0
	v_mov_b64_e32 v[50:51], 0
	v_mov_b64_e32 v[52:53], 0
	v_mov_b64_e32 v[54:55], 0
	v_mov_b64_e32 v[56:57], 0
	v_mov_b64_e32 v[58:59], 0
	v_mov_b64_e32 v[60:61], 0
	v_mov_b64_e32 v[62:63], 0
	v_mov_b64_e32 v[64:65], 0
	v_mov_b64_e32 v[66:67], 0
	v_mov_b64_e32 v[68:69], 0
	v_mov_b64_e32 v[70:71], 0
	v_mov_b64_e32 v[72:73], 0
	v_mov_b64_e32 v[74:75], 0
	v_mov_b64_e32 v[76:77], 0
	v_mov_b64_e32 v[78:79], 0
	v_mov_b64_e32 v[82:83], 0
	v_mov_b64_e32 v[84:85], 0
	v_mov_b64_e32 v[86:87], 0
	v_mov_b64_e32 v[88:89], 0
	v_mov_b64_e32 v[90:91], 0
	v_mov_b64_e32 v[92:93], 0
	v_mov_b64_e32 v[94:95], 0
	v_mov_b64_e32 v[96:97], 0
	v_mov_b64_e32 v[98:99], 0
	v_mov_b64_e32 v[100:101], 0
	v_mov_b64_e32 v[102:103], 0
	v_mov_b64_e32 v[104:105], 0
	v_mov_b64_e32 v[106:107], 0
	v_mov_b64_e32 v[108:109], 0
	v_mov_b64_e32 v[110:111], 0
	v_mov_b64_e32 v[112:113], 0
	v_mov_b64_e32 v[114:115], 0
	v_mov_b64_e32 v[116:117], 0
	v_mov_b64_e32 v[118:119], 0
	v_mov_b64_e32 v[120:121], 0
	v_mov_b64_e32 v[122:123], 0
	v_mov_b64_e32 v[124:125], 0
	v_mov_b64_e32 v[126:127], 0
	v_mov_b64_e32 v[128:129], 0
